# s5_prompt: pass 1's MW fragment loads issued spread through pass 0's gelu epilogue (exec-masked), on top of LRU prefetch placement and S5 blocked scan
# baseline (speedup 1.0000x reference)
; #define LAS __attribute__((address_space(3)))
; __device__ __forceinline__ unsigned cvt_pk_bf16(float lo, float hi) { unsigned r; asm("v_cvt_pk_bf16_f32 %0, %1, %2" : "=v"(r) : "v"(lo), "v"(hi)); return r; }
; __device__ __forceinline__ float fgelu(float x) { return x * fsigmoid(1.5957691216057308f * (x + 0.044715f * x * x * x)); }
; #define MFMA32(a, b, c) __builtin_amdgcn_mfma_f32_32x32x16_bf16((a), (b), (c), 0, 0, 0)
; __device__ __forceinline__ void s5_prompt(const Args& a, LAS unsigned char* lds, int b, int g, int tid, int lane, int wave) {
;     ...
; #pragma unroll 1
;     for (int pass = 0; pass < 2; ++pass) {
;         const int mt = pass ? 7 - wave : wave, n0 = 2 * pass;
;         const int nks = 2 * mt + 2;
;         const bf16_t* mw = MW + (size_t)(32 * mt + r32) * 384 + 8 * hh;
;         if (pass == 1) {
; #pragma unroll
;             for (int ks = 0; ks < 16; ++ks) if (ks < nks) am[ks] = *(const bf16x8*)(mw + 16 * ks);
; #pragma unroll
;             for (int kq = 0; kq < 8; ++kq) am[16 + kq] = *(const bf16x8*)(mw + 256 + 16 * kq);
;         }
;         if (pass == 0) __syncthreads();
;         f32x16 acc[2];
; #pragma unroll
;         for (int n = 0; n < 2; ++n)
; #pragma unroll
;             for (int i = 0; i < 16; ++i) acc[n][i] = 0.f;
; #pragma unroll
;         for (int ks = 0; ks < 16; ++ks) if (ks < nks) {
; #pragma unroll
;             for (int n = 0; n < 2; ++n) { const bf16x8 bf = *(const LAS bf16x8*)(XCs + (32 * (n0 + n) + r32) * S5_PITCH + 32 * ks + 16 * hh); acc[n] = MFMA32(am[ks], bf, acc[n]); }
;         }
; #pragma unroll
;         for (int kq = 0; kq < 8; ++kq) {
; #pragma unroll
;             for (int n = 0; n < 2; ++n) { const bf16x8 bf = *(const LAS bf16x8*)(ZS + (32 * (n0 + n) + r32) * S5_PITCH + 32 * kq + 16 * hh); acc[n] = MFMA32(am[16 + kq], bf, acc[n]); }
;         }
; #pragma unroll
;         for (int n = 0; n < 2; ++n)
; #pragma unroll
;             for (int q = 0; q < 4; ++q) {
;                 const int s = 2 * mt + (q >> 1), c0 = 8 * (q & 1) + 4 * hh, t = 16 * (32 * (n0 + n) + r32) + s;
;                 u32x2 w; w.x = cvt_pk_bf16(fgelu(acc[n][4 * q]), fgelu(acc[n][4 * q + 1])); w.y = cvt_pk_bf16(fgelu(acc[n][4 * q + 2]), fgelu(acc[n][4 * q + 3]));
;                 *(u32x2*)(GS5 + (size_t)(b * SEQ + t) * DH + 16 * g + c0) = w;
;             }
.LBB0_593:
	v_add_u32_e32 v46, v196, v34
	ds_read_b128 v[38:41], v46
	ds_read_b128 v[42:45], v46 offset:32
	v_add_u32_e32 v47, v196, v36
	s_mov_b64 s[36:37], 0
	v_readlane_b32 s100, v254, 12
	s_lshr_b32 s100, s100, 6
	s_mul_i32 s48, s34, 0x6000
	s_add_u32 s48, s50, s48
	s_addc_u32 s49, s51, 0
	s_andn2_b64 vcc, exec, s[6:7]
	s_cselect_b32 s100, s100, 99
	s_waitcnt vmcnt(7) lgkmcnt(1)
	v_mfma_f32_32x32x16_bf16 v[2:17], v[130:133], v[38:41], v[2:17]
	ds_read_b128 v[34:37], v47
	ds_read_b128 v[38:41], v47 offset:32
	s_waitcnt lgkmcnt(1)
	v_mfma_f32_32x32x16_bf16 v[18:33], v[130:133], v[34:37], v[18:33]
	ds_read_b128 v[34:37], v46 offset:64
	s_waitcnt vmcnt(6)
	v_mfma_f32_32x32x16_bf16 v[2:17], v[134:137], v[42:45], v[2:17]
	s_waitcnt lgkmcnt(1)
	v_mfma_f32_32x32x16_bf16 v[18:33], v[134:137], v[38:41], v[18:33]
	s_waitcnt vmcnt(5) lgkmcnt(0)
	v_mfma_f32_32x32x16_bf16 v[2:17], v[138:141], v[34:37], v[2:17]
	ds_read_b128 v[34:37], v47 offset:64
	s_waitcnt lgkmcnt(0)
	v_mfma_f32_32x32x16_bf16 v[18:33], v[138:141], v[34:37], v[18:33]
	ds_read_b128 v[34:37], v46 offset:96
	s_waitcnt vmcnt(4) lgkmcnt(0)
	v_mfma_f32_32x32x16_bf16 v[2:17], v[142:145], v[34:37], v[2:17]
	ds_read_b128 v[34:37], v47 offset:96
	s_waitcnt lgkmcnt(0)
	v_mfma_f32_32x32x16_bf16 v[18:33], v[142:145], v[34:37], v[18:33]
	ds_read_b128 v[34:37], v46 offset:128
	s_waitcnt vmcnt(3) lgkmcnt(0)
	v_mfma_f32_32x32x16_bf16 v[2:17], v[146:149], v[34:37], v[2:17]
	ds_read_b128 v[34:37], v47 offset:128
	s_waitcnt lgkmcnt(0)
	v_mfma_f32_32x32x16_bf16 v[18:33], v[146:149], v[34:37], v[18:33]
	ds_read_b128 v[34:37], v46 offset:160
	s_waitcnt vmcnt(2) lgkmcnt(0)
	v_mfma_f32_32x32x16_bf16 v[2:17], v[150:153], v[34:37], v[2:17]
	ds_read_b128 v[34:37], v47 offset:160
	s_waitcnt lgkmcnt(0)
	v_mfma_f32_32x32x16_bf16 v[18:33], v[150:153], v[34:37], v[18:33]
	ds_read_b128 v[34:37], v46 offset:192
	s_waitcnt vmcnt(1) lgkmcnt(0)
	v_mfma_f32_32x32x16_bf16 v[2:17], v[154:157], v[34:37], v[2:17]
	ds_read_b128 v[34:37], v47 offset:192
	s_waitcnt lgkmcnt(0)
	v_mfma_f32_32x32x16_bf16 v[18:33], v[154:157], v[34:37], v[18:33]
	ds_read_b128 v[34:37], v46 offset:224
	s_waitcnt vmcnt(0) lgkmcnt(0)
	v_mfma_f32_32x32x16_bf16 v[2:17], v[158:161], v[34:37], v[2:17]
	ds_read_b128 v[34:37], v47 offset:224
	s_waitcnt lgkmcnt(0)
	v_mfma_f32_32x32x16_bf16 v[18:33], v[158:161], v[34:37], v[18:33]
	s_nop 8
	v_mul_f32_e32 v35, 0x3d372713, v2
	v_mul_f32_e32 v35, v2, v35
	v_fma_f32 v35, v2, v35, v2
	v_mul_f32_e32 v35, 0x3fcc422a, v35
	v_mul_f32_e32 v35, 0xbfb8aa3b, v35
	v_exp_f32_e32 v35, v35
	v_lshl_add_u32 v36, s78, 1, v213
	v_lshl_add_u32 v34, s44, 10, v36
	s_mov_b32 s44, 1
	v_add_f32_e32 v35, 1.0, v35
	v_rcp_f32_e32 v35, v35
	s_nop 0
	v_mul_f32_e32 v2, v2, v35
	v_mul_f32_e32 v35, 0x3d372713, v3
	v_mul_f32_e32 v35, v3, v35
	v_fma_f32 v35, v3, v35, v3
	v_mul_f32_e32 v35, 0x3fcc422a, v35
	v_mul_f32_e32 v35, 0xbfb8aa3b, v35
	v_exp_f32_e32 v35, v35
	s_nop 0
	v_add_f32_e32 v35, 1.0, v35
	v_rcp_f32_e32 v35, v35
	s_nop 0
	v_mul_f32_e32 v3, v3, v35
	v_cvt_pk_bf16_f32 v38, v2, v3
	s_cmp_lt_u32 s100, 8
	s_cselect_b64 exec, -1, 0
	global_load_dwordx4 v[66:69], v225, s[48:49]
	global_load_dwordx4 v[70:73], v225, s[48:49] offset:1024
	s_mov_b64 exec, -1
	v_mul_f32_e32 v2, 0x3d372713, v4
	v_mul_f32_e32 v3, 0x3d372713, v5
	v_mul_f32_e32 v2, v4, v2
	v_mul_f32_e32 v3, v5, v3
	v_fma_f32 v2, v4, v2, v4
	v_fma_f32 v3, v5, v3, v5
	v_mul_f32_e32 v2, 0x3fcc422a, v2
	v_mul_f32_e32 v3, 0x3fcc422a, v3
	v_mul_f32_e32 v2, 0xbfb8aa3b, v2
	v_mul_f32_e32 v3, 0xbfb8aa3b, v3
	v_exp_f32_e32 v2, v2
	v_exp_f32_e32 v3, v3
	v_ashrrev_i32_e32 v35, 31, v34
	v_add_f32_e32 v2, 1.0, v2
	v_add_f32_e32 v3, 1.0, v3
	v_rcp_f32_e32 v2, v2
	v_rcp_f32_e32 v3, v3
	v_mul_f32_e32 v2, v4, v2
	v_mul_f32_e32 v3, v5, v3
	v_mul_f32_e32 v4, 0x3d372713, v6
	v_mul_f32_e32 v5, 0x3d372713, v7
	v_mul_f32_e32 v4, v6, v4
	v_mul_f32_e32 v5, v7, v5
	v_fma_f32 v4, v6, v4, v6
	v_fma_f32 v5, v7, v5, v7
	v_mul_f32_e32 v4, 0x3fcc422a, v4
	s_cmp_lt_u32 s100, 7
	s_cselect_b64 exec, -1, 0
	global_load_dwordx4 v[74:77], v225, s[48:49] offset:2048
	global_load_dwordx4 v[78:81], v225, s[48:49] offset:3072
	s_mov_b64 exec, -1
	v_mul_f32_e32 v5, 0x3fcc422a, v5
	v_mul_f32_e32 v4, 0xbfb8aa3b, v4
	v_mul_f32_e32 v5, 0xbfb8aa3b, v5
	v_exp_f32_e32 v4, v4
	v_exp_f32_e32 v5, v5
	v_cvt_pk_bf16_f32 v39, v2, v3
	v_lshlrev_b64 v[2:3], 11, v[34:35]
	v_add_f32_e32 v4, 1.0, v4
	v_add_f32_e32 v5, 1.0, v5
	v_rcp_f32_e32 v4, v4
	v_rcp_f32_e32 v5, v5
	v_lshl_add_u64 v[2:3], v[180:181], 0, v[2:3]
	global_store_dwordx2 v[2:3], v[38:39], off
	v_mul_f32_e32 v4, v6, v4
	v_mul_f32_e32 v5, v7, v5
	v_cvt_pk_bf16_f32 v4, v4, v5
	v_mul_f32_e32 v5, 0x3d372713, v8
	v_mul_f32_e32 v5, v8, v5
	v_mul_f32_e32 v6, 0x3d372713, v9
	v_fma_f32 v5, v8, v5, v8
	v_mul_f32_e32 v6, v9, v6
	v_mul_f32_e32 v5, 0x3fcc422a, v5
	s_cmp_lt_u32 s100, 6
	s_cselect_b64 exec, -1, 0
	global_load_dwordx4 v[82:85], v226, s[48:49]
	global_load_dwordx4 v[86:89], v226, s[48:49] offset:1024
	s_mov_b64 exec, -1
	v_fma_f32 v6, v9, v6, v9
	v_mul_f32_e32 v5, 0xbfb8aa3b, v5
	v_mul_f32_e32 v6, 0x3fcc422a, v6
	v_exp_f32_e32 v5, v5
	v_mul_f32_e32 v6, 0xbfb8aa3b, v6
	v_exp_f32_e32 v6, v6
	v_add_f32_e32 v5, 1.0, v5
	v_rcp_f32_e32 v5, v5
	v_add_f32_e32 v6, 1.0, v6
	v_rcp_f32_e32 v6, v6
	v_mul_f32_e32 v5, v8, v5
	v_mul_f32_e32 v6, v9, v6
	v_cvt_pk_bf16_f32 v5, v5, v6
	global_store_dwordx2 v[2:3], v[4:5], off offset:16
	v_mul_f32_e32 v2, 0x3d372713, v10
	v_mul_f32_e32 v3, 0x3d372713, v11
	v_mul_f32_e32 v2, v10, v2
	v_mul_f32_e32 v3, v11, v3
	v_fma_f32 v2, v10, v2, v10
	v_fma_f32 v3, v11, v3, v11
	v_mul_f32_e32 v2, 0x3fcc422a, v2
	v_mul_f32_e32 v3, 0x3fcc422a, v3
; #define LAS __attribute__((address_space(3)))
; __device__ __forceinline__ unsigned cvt_pk_bf16(float lo, float hi) { unsigned r; asm("v_cvt_pk_bf16_f32 %0, %1, %2" : "=v"(r) : "v"(lo), "v"(hi)); return r; }
; __device__ __forceinline__ float fgelu(float x) { return x * fsigmoid(1.5957691216057308f * (x + 0.044715f * x * x * x)); }
; #define MFMA32(a, b, c) __builtin_amdgcn_mfma_f32_32x32x16_bf16((a), (b), (c), 0, 0, 0)
; __device__ __forceinline__ void s5_prompt(const Args& a, LAS unsigned char* lds, int b, int g, int tid, int lane, int wave) {
;     ...
; #pragma unroll 1
;     for (int pass = 0; pass < 2; ++pass) {
;         const int mt = pass ? 7 - wave : wave, n0 = 2 * pass;
;         const int nks = 2 * mt + 2;
;         const bf16_t* mw = MW + (size_t)(32 * mt + r32) * 384 + 8 * hh;
;         if (pass == 1) {
; #pragma unroll
;             for (int ks = 0; ks < 16; ++ks) if (ks < nks) am[ks] = *(const bf16x8*)(mw + 16 * ks);
; #pragma unroll
;             for (int kq = 0; kq < 8; ++kq) am[16 + kq] = *(const bf16x8*)(mw + 256 + 16 * kq);
;         }
;         if (pass == 0) __syncthreads();
;         f32x16 acc[2];
; #pragma unroll
;         for (int n = 0; n < 2; ++n)
; #pragma unroll
;             for (int i = 0; i < 16; ++i) acc[n][i] = 0.f;
; #pragma unroll
;         for (int ks = 0; ks < 16; ++ks) if (ks < nks) {
; #pragma unroll
;             for (int n = 0; n < 2; ++n) { const bf16x8 bf = *(const LAS bf16x8*)(XCs + (32 * (n0 + n) + r32) * S5_PITCH + 32 * ks + 16 * hh); acc[n] = MFMA32(am[ks], bf, acc[n]); }
;         }
; #pragma unroll
;         for (int kq = 0; kq < 8; ++kq) {
; #pragma unroll
;             for (int n = 0; n < 2; ++n) { const bf16x8 bf = *(const LAS bf16x8*)(ZS + (32 * (n0 + n) + r32) * S5_PITCH + 32 * kq + 16 * hh); acc[n] = MFMA32(am[16 + kq], bf, acc[n]); }
;         }
; #pragma unroll
;         for (int n = 0; n < 2; ++n)
; #pragma unroll
;             for (int q = 0; q < 4; ++q) {
;                 const int s = 2 * mt + (q >> 1), c0 = 8 * (q & 1) + 4 * hh, t = 16 * (32 * (n0 + n) + r32) + s;
;                 u32x2 w; w.x = cvt_pk_bf16(fgelu(acc[n][4 * q]), fgelu(acc[n][4 * q + 1])); w.y = cvt_pk_bf16(fgelu(acc[n][4 * q + 2]), fgelu(acc[n][4 * q + 3]));
;                 *(u32x2*)(GS5 + (size_t)(b * SEQ + t) * DH + 16 * g + c0) = w;
;             }
	v_mul_f32_e32 v2, 0xbfb8aa3b, v2
	v_mul_f32_e32 v3, 0xbfb8aa3b, v3
	v_exp_f32_e32 v2, v2
	s_cmp_lt_u32 s100, 5
	s_cselect_b64 exec, -1, 0
	global_load_dwordx4 v[90:93], v226, s[48:49] offset:2048
	global_load_dwordx4 v[94:97], v226, s[48:49] offset:3072
	s_mov_b64 exec, -1
	v_exp_f32_e32 v3, v3
	v_mul_f32_e32 v4, 0x3d372713, v13
	v_mul_f32_e32 v4, v13, v4
	v_add_f32_e32 v2, 1.0, v2
	v_add_f32_e32 v3, 1.0, v3
	v_rcp_f32_e32 v2, v2
	v_rcp_f32_e32 v3, v3
	v_fma_f32 v4, v13, v4, v13
	v_mul_f32_e32 v4, 0x3fcc422a, v4
	v_mul_f32_e32 v2, v10, v2
	v_mul_f32_e32 v3, v11, v3
	v_cvt_pk_bf16_f32 v2, v2, v3
	v_mul_f32_e32 v3, 0x3d372713, v12
	v_mul_f32_e32 v3, v12, v3
	v_fma_f32 v3, v12, v3, v12
	v_mul_f32_e32 v3, 0x3fcc422a, v3
	v_mul_f32_e32 v3, 0xbfb8aa3b, v3
	v_mul_f32_e32 v4, 0xbfb8aa3b, v4
	v_exp_f32_e32 v3, v3
	v_exp_f32_e32 v4, v4
	v_mul_f32_e32 v6, 0x3d372713, v17
	v_mul_f32_e32 v6, v17, v6
	v_add_f32_e32 v3, 1.0, v3
	v_add_f32_e32 v4, 1.0, v4
	s_cmp_lt_u32 s100, 4
	s_cselect_b64 exec, -1, 0
	global_load_dwordx4 v[98:101], v227, s[48:49]
	global_load_dwordx4 v[102:105], v227, s[48:49] offset:1024
	s_mov_b64 exec, -1
	v_rcp_f32_e32 v3, v3
	v_rcp_f32_e32 v4, v4
	v_fma_f32 v6, v17, v6, v17
	v_mul_f32_e32 v6, 0x3fcc422a, v6
	v_mul_f32_e32 v3, v12, v3
	v_mul_f32_e32 v4, v13, v4
	v_cvt_pk_bf16_f32 v3, v3, v4
	v_or_b32_e32 v4, 1, v34
	v_ashrrev_i32_e32 v5, 31, v4
	v_lshlrev_b64 v[4:5], 11, v[4:5]
	v_lshl_add_u64 v[4:5], v[180:181], 0, v[4:5]
	global_store_dwordx2 v[4:5], v[2:3], off
	v_mul_f32_e32 v2, 0x3d372713, v14
	v_mul_f32_e32 v3, 0x3d372713, v15
	v_mul_f32_e32 v2, v14, v2
	v_mul_f32_e32 v3, v15, v3
	v_fma_f32 v2, v14, v2, v14
	v_fma_f32 v3, v15, v3, v15
	v_mul_f32_e32 v2, 0x3fcc422a, v2
	v_mul_f32_e32 v3, 0x3fcc422a, v3
	v_mul_f32_e32 v2, 0xbfb8aa3b, v2
	v_mul_f32_e32 v3, 0xbfb8aa3b, v3
	v_exp_f32_e32 v2, v2
	v_exp_f32_e32 v3, v3
	s_cmp_lt_u32 s100, 3
	s_cselect_b64 exec, -1, 0
	global_load_dwordx4 v[106:109], v227, s[48:49] offset:2048
	global_load_dwordx4 v[110:113], v227, s[48:49] offset:3072
	s_mov_b64 exec, -1
	v_mul_f32_e32 v6, 0xbfb8aa3b, v6
	v_exp_f32_e32 v6, v6
	v_add_f32_e32 v2, 1.0, v2
	v_add_f32_e32 v3, 1.0, v3
	v_rcp_f32_e32 v2, v2
	v_rcp_f32_e32 v3, v3
	v_add_f32_e32 v6, 1.0, v6
	v_rcp_f32_e32 v6, v6
	v_mul_f32_e32 v2, v14, v2
	v_mul_f32_e32 v3, v15, v3
	v_cvt_pk_bf16_f32 v2, v2, v3
	v_mul_f32_e32 v3, 0x3d372713, v16
	v_mul_f32_e32 v3, v16, v3
	v_fma_f32 v3, v16, v3, v16
	v_mul_f32_e32 v3, 0x3fcc422a, v3
	v_mul_f32_e32 v3, 0xbfb8aa3b, v3
	v_exp_f32_e32 v3, v3
	v_mul_f32_e32 v6, v17, v6
	v_add_f32_e32 v3, 1.0, v3
	v_rcp_f32_e32 v3, v3
	s_nop 0
	v_mul_f32_e32 v3, v16, v3
	v_cvt_pk_bf16_f32 v3, v3, v6
	s_cmp_lt_u32 s100, 2
	s_cselect_b64 exec, -1, 0
	global_load_dwordx4 v[114:117], v228, s[48:49]
	global_load_dwordx4 v[118:121], v228, s[48:49] offset:1024
	s_mov_b64 exec, -1
	global_store_dwordx2 v[4:5], v[2:3], off offset:16
	v_mul_f32_e32 v3, 0x3d372713, v18
	v_mul_f32_e32 v4, 0x3d372713, v19
	v_mul_f32_e32 v3, v18, v3
	v_mul_f32_e32 v4, v19, v4
	v_fma_f32 v3, v18, v3, v18
	v_fma_f32 v4, v19, v4, v19
	v_mul_f32_e32 v3, 0x3fcc422a, v3
	v_mul_f32_e32 v4, 0x3fcc422a, v4
	v_mul_f32_e32 v3, 0xbfb8aa3b, v3
	v_mul_f32_e32 v4, 0xbfb8aa3b, v4
	v_exp_f32_e32 v3, v3
	v_exp_f32_e32 v4, v4
	v_mul_f32_e32 v5, 0x3d372713, v21
	v_mul_f32_e32 v5, v21, v5
	v_add_f32_e32 v3, 1.0, v3
	v_add_f32_e32 v4, 1.0, v4
	v_rcp_f32_e32 v3, v3
	v_rcp_f32_e32 v4, v4
	v_fma_f32 v5, v21, v5, v21
	v_mul_f32_e32 v5, 0x3fcc422a, v5
	v_mul_f32_e32 v3, v18, v3
	v_mul_f32_e32 v4, v19, v4
	v_cvt_pk_bf16_f32 v4, v3, v4
	s_cmp_lt_u32 s100, 1
	s_cselect_b64 exec, -1, 0
	global_load_dwordx4 v[122:125], v228, s[48:49] offset:2048
	global_load_dwordx4 v[126:129], v228, s[48:49] offset:3072
	s_mov_b64 exec, -1
	v_mul_f32_e32 v3, 0x3d372713, v20
	v_mul_f32_e32 v3, v20, v3
	v_fma_f32 v3, v20, v3, v20
	v_mul_f32_e32 v3, 0x3fcc422a, v3
	v_mul_f32_e32 v3, 0xbfb8aa3b, v3
	v_mul_f32_e32 v5, 0xbfb8aa3b, v5
	v_exp_f32_e32 v3, v3
	v_exp_f32_e32 v5, v5
	v_lshl_add_u32 v2, s76, 9, v36
	s_mov_b64 s[76:77], -1
	v_add_f32_e32 v3, 1.0, v3
	v_add_f32_e32 v5, 1.0, v5
	v_rcp_f32_e32 v3, v3
	v_rcp_f32_e32 v5, v5
	v_mul_f32_e32 v3, v20, v3
	v_mul_f32_e32 v5, v21, v5
	v_cvt_pk_bf16_f32 v5, v3, v5
	v_ashrrev_i32_e32 v3, 31, v2
	v_lshlrev_b64 v[6:7], 11, v[2:3]
	v_lshl_add_u64 v[6:7], v[180:181], 0, v[6:7]
; #define LAS __attribute__((address_space(3)))
; __device__ __forceinline__ unsigned cvt_pk_bf16(float lo, float hi) { unsigned r; asm("v_cvt_pk_bf16_f32 %0, %1, %2" : "=v"(r) : "v"(lo), "v"(hi)); return r; }
; __device__ __forceinline__ float fgelu(float x) { return x * fsigmoid(1.5957691216057308f * (x + 0.044715f * x * x * x)); }
; #define MFMA32(a, b, c) __builtin_amdgcn_mfma_f32_32x32x16_bf16((a), (b), (c), 0, 0, 0)
; __device__ __forceinline__ void s5_prompt(const Args& a, LAS unsigned char* lds, int b, int g, int tid, int lane, int wave) {
;     ...
; #pragma unroll 1
;     for (int pass = 0; pass < 2; ++pass) {
;         const int mt = pass ? 7 - wave : wave, n0 = 2 * pass;
;         const int nks = 2 * mt + 2;
;         const bf16_t* mw = MW + (size_t)(32 * mt + r32) * 384 + 8 * hh;
;         if (pass == 1) {
; #pragma unroll
;             for (int ks = 0; ks < 16; ++ks) if (ks < nks) am[ks] = *(const bf16x8*)(mw + 16 * ks);
; #pragma unroll
;             for (int kq = 0; kq < 8; ++kq) am[16 + kq] = *(const bf16x8*)(mw + 256 + 16 * kq);
;         }
;         if (pass == 0) __syncthreads();
;         f32x16 acc[2];
; #pragma unroll
;         for (int n = 0; n < 2; ++n)
; #pragma unroll
;             for (int i = 0; i < 16; ++i) acc[n][i] = 0.f;
; #pragma unroll
;         for (int ks = 0; ks < 16; ++ks) if (ks < nks) {
; #pragma unroll
;             for (int n = 0; n < 2; ++n) { const bf16x8 bf = *(const LAS bf16x8*)(XCs + (32 * (n0 + n) + r32) * S5_PITCH + 32 * ks + 16 * hh); acc[n] = MFMA32(am[ks], bf, acc[n]); }
;         }
; #pragma unroll
;         for (int kq = 0; kq < 8; ++kq) {
; #pragma unroll
;             for (int n = 0; n < 2; ++n) { const bf16x8 bf = *(const LAS bf16x8*)(ZS + (32 * (n0 + n) + r32) * S5_PITCH + 32 * kq + 16 * hh); acc[n] = MFMA32(am[16 + kq], bf, acc[n]); }
;         }
; #pragma unroll
;         for (int n = 0; n < 2; ++n)
; #pragma unroll
;             for (int q = 0; q < 4; ++q) {
;                 const int s = 2 * mt + (q >> 1), c0 = 8 * (q & 1) + 4 * hh, t = 16 * (32 * (n0 + n) + r32) + s;
;                 u32x2 w; w.x = cvt_pk_bf16(fgelu(acc[n][4 * q]), fgelu(acc[n][4 * q + 1])); w.y = cvt_pk_bf16(fgelu(acc[n][4 * q + 2]), fgelu(acc[n][4 * q + 3]));
;                 *(u32x2*)(GS5 + (size_t)(b * SEQ + t) * DH + 16 * g + c0) = w;
;             }
	global_store_dwordx2 v[6:7], v[4:5], off
	v_mul_f32_e32 v3, 0x3d372713, v22
	v_mul_f32_e32 v4, 0x3d372713, v23
	v_mul_f32_e32 v3, v22, v3
	s_cmp_lt_u32 s100, 8
	s_cselect_b64 exec, -1, 0
	global_load_dwordx4 v[130:133], v229, s[48:49]
	global_load_dwordx4 v[134:137], v229, s[48:49] offset:1024
	s_mov_b64 exec, -1
	v_mul_f32_e32 v4, v23, v4
	v_fma_f32 v3, v22, v3, v22
	v_fma_f32 v4, v23, v4, v23
	v_mul_f32_e32 v3, 0x3fcc422a, v3
	v_mul_f32_e32 v4, 0x3fcc422a, v4
	v_mul_f32_e32 v3, 0xbfb8aa3b, v3
	v_mul_f32_e32 v4, 0xbfb8aa3b, v4
	v_exp_f32_e32 v3, v3
	v_exp_f32_e32 v4, v4
	v_mul_f32_e32 v5, 0x3d372713, v25
	v_mul_f32_e32 v5, v25, v5
	v_add_f32_e32 v3, 1.0, v3
	v_add_f32_e32 v4, 1.0, v4
	v_rcp_f32_e32 v3, v3
	v_rcp_f32_e32 v4, v4
	v_fma_f32 v5, v25, v5, v25
	v_mul_f32_e32 v5, 0x3fcc422a, v5
	v_mul_f32_e32 v3, v22, v3
	v_mul_f32_e32 v4, v23, v4
	v_cvt_pk_bf16_f32 v4, v3, v4
	v_mul_f32_e32 v3, 0x3d372713, v24
	v_mul_f32_e32 v3, v24, v3
	v_fma_f32 v3, v24, v3, v24
	v_mul_f32_e32 v3, 0x3fcc422a, v3
	s_cmp_lt_u32 s100, 8
	s_cselect_b64 exec, -1, 0
	global_load_dwordx4 v[138:141], v229, s[48:49] offset:2048
	global_load_dwordx4 v[142:145], v229, s[48:49] offset:3072
	s_mov_b64 exec, -1
	v_mul_f32_e32 v3, 0xbfb8aa3b, v3
	v_mul_f32_e32 v5, 0xbfb8aa3b, v5
	v_exp_f32_e32 v3, v3
	v_exp_f32_e32 v5, v5
	v_or_b32_e32 v2, 1, v2
	v_add_f32_e32 v3, 1.0, v3
	v_add_f32_e32 v5, 1.0, v5
	v_rcp_f32_e32 v3, v3
	v_rcp_f32_e32 v5, v5
	v_mul_f32_e32 v3, v24, v3
	v_mul_f32_e32 v5, v25, v5
	v_cvt_pk_bf16_f32 v5, v3, v5
	global_store_dwordx2 v[6:7], v[4:5], off offset:16
	v_mul_f32_e32 v3, 0x3d372713, v26
	v_mul_f32_e32 v4, 0x3d372713, v27
	v_mul_f32_e32 v3, v26, v3
	v_mul_f32_e32 v4, v27, v4
	v_fma_f32 v3, v26, v3, v26
	v_fma_f32 v4, v27, v4, v27
	v_mul_f32_e32 v3, 0x3fcc422a, v3
	v_mul_f32_e32 v4, 0x3fcc422a, v4
	v_mul_f32_e32 v3, 0xbfb8aa3b, v3
	v_mul_f32_e32 v4, 0xbfb8aa3b, v4
	v_exp_f32_e32 v3, v3
	v_exp_f32_e32 v4, v4
	s_cmp_lt_u32 s100, 8
	s_cselect_b64 exec, -1, 0
	global_load_dwordx4 v[146:149], v230, s[48:49]
	global_load_dwordx4 v[150:153], v230, s[48:49] offset:1024
	s_mov_b64 exec, -1
	v_mul_f32_e32 v5, 0x3d372713, v29
	v_mul_f32_e32 v5, v29, v5
	v_add_f32_e32 v3, 1.0, v3
	v_add_f32_e32 v4, 1.0, v4
	v_rcp_f32_e32 v3, v3
	v_rcp_f32_e32 v4, v4
	v_fma_f32 v5, v29, v5, v29
	v_mul_f32_e32 v5, 0x3fcc422a, v5
	v_mul_f32_e32 v3, v26, v3
	v_mul_f32_e32 v4, v27, v4
	v_cvt_pk_bf16_f32 v4, v3, v4
	v_mul_f32_e32 v3, 0x3d372713, v28
	v_mul_f32_e32 v3, v28, v3
	v_fma_f32 v3, v28, v3, v28
	v_mul_f32_e32 v3, 0x3fcc422a, v3
	v_mul_f32_e32 v3, 0xbfb8aa3b, v3
	v_mul_f32_e32 v5, 0xbfb8aa3b, v5
	v_exp_f32_e32 v3, v3
	v_exp_f32_e32 v5, v5
	v_mul_f32_e32 v6, 0x3d372713, v33
	v_mul_f32_e32 v6, v33, v6
	v_add_f32_e32 v3, 1.0, v3
	v_add_f32_e32 v5, 1.0, v5
	v_rcp_f32_e32 v3, v3
	s_cmp_lt_u32 s100, 8
	s_cselect_b64 exec, -1, 0
	global_load_dwordx4 v[154:157], v230, s[48:49] offset:2048
	global_load_dwordx4 v[158:161], v230, s[48:49] offset:3072
	s_mov_b64 exec, -1
	v_rcp_f32_e32 v5, v5
	v_fma_f32 v6, v33, v6, v33
	v_mul_f32_e32 v6, 0x3fcc422a, v6
	v_mul_f32_e32 v3, v28, v3
	v_mul_f32_e32 v5, v29, v5
	v_cvt_pk_bf16_f32 v5, v3, v5
	v_ashrrev_i32_e32 v3, 31, v2
	v_lshlrev_b64 v[2:3], 11, v[2:3]
	v_lshl_add_u64 v[2:3], v[180:181], 0, v[2:3]
	global_store_dwordx2 v[2:3], v[4:5], off
	v_mul_f32_e32 v4, 0x3d372713, v30
	v_mul_f32_e32 v5, 0x3d372713, v31
	v_mul_f32_e32 v4, v30, v4
	v_mul_f32_e32 v5, v31, v5
	v_fma_f32 v4, v30, v4, v30
	v_fma_f32 v5, v31, v5, v31
	v_mul_f32_e32 v4, 0x3fcc422a, v4
	v_mul_f32_e32 v5, 0x3fcc422a, v5
	v_mul_f32_e32 v4, 0xbfb8aa3b, v4
	v_mul_f32_e32 v5, 0xbfb8aa3b, v5
	v_exp_f32_e32 v4, v4
	v_exp_f32_e32 v5, v5
	v_mul_f32_e32 v6, 0xbfb8aa3b, v6
	v_exp_f32_e32 v6, v6
	v_add_f32_e32 v4, 1.0, v4
	v_add_f32_e32 v5, 1.0, v5
	v_rcp_f32_e32 v4, v4
	v_rcp_f32_e32 v5, v5
	v_add_f32_e32 v6, 1.0, v6
	v_rcp_f32_e32 v6, v6
	v_mul_f32_e32 v4, v30, v4
	v_mul_f32_e32 v5, v31, v5
	v_cvt_pk_bf16_f32 v4, v4, v5
	v_mul_f32_e32 v5, 0x3d372713, v32
	v_mul_f32_e32 v5, v32, v5
	v_fma_f32 v5, v32, v5, v32
	v_mul_f32_e32 v5, 0x3fcc422a, v5
	v_mul_f32_e32 v5, 0xbfb8aa3b, v5
	v_exp_f32_e32 v5, v5
	v_mul_f32_e32 v6, v33, v6
	v_add_f32_e32 v5, 1.0, v5
	v_rcp_f32_e32 v5, v5
	s_nop 0
	v_mul_f32_e32 v5, v32, v5
	v_cvt_pk_bf16_f32 v5, v5, v6
	global_store_dwordx2 v[2:3], v[4:5], off offset:16
	s_cbranch_vccz .LBB0_558

; __device__ __forceinline__ void s5_prompt(const Args& a, LAS unsigned char* lds, int b, int g, int tid, int lane, int wave) {
;     ...
;         if (pass == 1) {
; #pragma unroll
;             for (int ks = 0; ks < 16; ++ks) if (ks < nks) am[ks] = *(const bf16x8*)(mw + 16 * ks);
; #pragma unroll
;             for (int kq = 0; kq < 8; ++kq) am[16 + kq] = *(const bf16x8*)(mw + 256 + 16 * kq);
;         }
.LBB0_596:
	s_andn2_b64 vcc, exec, s[6:7]
	s_branch .LBB0_630
